# SWA attention: K/V staging rewritten by hand (10 global loads in flight, then LDS stores) replacing load-wait-store loops; 4 key-position loads per block issued together
# speedup vs baseline: 1.0475x; 1.0076x over previous
; #define LAS __attribute__((address_space(3)))
; DI void swa_attn_phase(const Params& p, LAS unsigned char* lds) {
;     ...
;     for (int it0 = bid; it0 < 2048; it0 += gridDim.x) {
;         const int item = (gridDim.x == 256) ? (((it0 >> 8) * 8 + (it0 & 7)) * 32 + ((it0 & 255) >> 3)) : it0;
;         const int b = item >> 9, kvh = (item >> 7) & 3, qb = item & 127, q0 = qb * 32, kstart = q0 - 128;
;         const bf16_t* Kg = KS + (size_t)(b * 4 + kvh) * S * 64; const bf16_t* Vg = VTS + (size_t)(b * 4 + kvh) * 64 * S;
;         for (int c = tid; c < 2304; c += 512) { const int row = c >> 3, cc = c & 7, key = kstart + row;
;             if (key >= 0 && key < S) *(LAS u32x4*)(lds + row * KSTR + cc * 16) = *(const u32x4*)(Kg + (size_t)key * 64 + cc * 8); }
;         for (int c = tid; c < 2304; c += 512) { const int row = c / 36, cc = c - row * 36, key0 = kstart + cc * 8;
;             if (key0 >= 0 && key0 < S) { const u32x4 v = *(const u32x4*)(Vg + (size_t)row * S + key0);
;                 LAS u32x2* dp = (LAS u32x2*)(lds + VOFF + row * VSTR + (cc >> 1) * 32 + (cc & 1) * 8); dp[0] = (u32x2){v[0], v[1]}; dp[2] = (u32x2){v[2], v[3]}; } }
.LBB1_839:
	s_lshl_b32 s3, s2, 5
	s_and_b32 s3, s3, 0xe0
	s_and_b32 s12, s2, 0xffffff00
	s_or_b32 s3, s3, s12
	s_bfe_u32 s12, s2, 0x50003
	s_or_b32 s3, s3, s12
	v_readlane_b32 s12, v246, 54
	v_readlane_b32 s13, v246, 55
	s_and_b64 s[12:13], s[12:13], exec
	s_cselect_b32 s12, s3, s2
	s_ashr_i32 s3, s12, 9
	s_bfe_u32 s25, s12, 0x20007
	s_lshl_b32 s12, s12, 5
	s_and_b32 s24, s12, 0xfe0
	s_add_i32 s23, s24, 0xffffff80
	s_and_saveexec_b64 s[12:13], s[40:41]
	s_cbranch_execz .LBB1_848
	s_lshl_b32 s14, s3, 2
	s_or_b32 s14, s14, s25
	s_ashr_i32 s15, s14, 31
	s_lshl_b64 s[14:15], s[14:15], 19
	v_lshl_add_u64 v[188:189], v[68:69], 0, s[14:15]
	s_add_u32 s16, s4, s14
	s_addc_u32 s17, s5, s15
	v_mov_b32_e32 v177, 0
	s_movk_i32 s26, 0x90
	v_mov_b32_e32 v172, v67
	v_ashrrev_i32_e32 v173, 3, v172
	v_add_u32_e32 v174, s23, v173
	v_mad_u32_u24 v187, v173, s26, v70
	v_lshlrev_b32_e32 v176, 7, v174
	v_cmp_gt_u32_e32 vcc, s20, v174
	s_nop 1
	v_cndmask_b32_e32 v160, -1, v187, vcc
	s_and_saveexec_b64 s[18:19], vcc
	v_lshl_add_u64 v[178:179], v[188:189], 0, v[176:177]
	global_load_dwordx4 v[120:123], v[178:179], off
	s_mov_b64 exec, s[18:19]
	v_add_u32_e32 v172, 512, v67
	v_ashrrev_i32_e32 v173, 3, v172
	v_add_u32_e32 v174, s23, v173
	v_mad_u32_u24 v187, v173, s26, v70
	v_lshlrev_b32_e32 v176, 7, v174
	v_cmp_gt_u32_e32 vcc, s20, v174
	s_nop 1
	v_cndmask_b32_e32 v161, -1, v187, vcc
	s_and_saveexec_b64 s[18:19], vcc
	v_lshl_add_u64 v[178:179], v[188:189], 0, v[176:177]
	global_load_dwordx4 v[124:127], v[178:179], off
	s_mov_b64 exec, s[18:19]
	v_add_u32_e32 v172, 1024, v67
	v_ashrrev_i32_e32 v173, 3, v172
	v_add_u32_e32 v174, s23, v173
	v_mad_u32_u24 v187, v173, s26, v70
	v_lshlrev_b32_e32 v176, 7, v174
	v_cmp_gt_u32_e32 vcc, s20, v174
	s_nop 1
	v_cndmask_b32_e32 v162, -1, v187, vcc
	s_and_saveexec_b64 s[18:19], vcc
	v_lshl_add_u64 v[178:179], v[188:189], 0, v[176:177]
	global_load_dwordx4 v[128:131], v[178:179], off
	s_mov_b64 exec, s[18:19]
	v_add_u32_e32 v172, 1536, v67
	v_ashrrev_i32_e32 v173, 3, v172
	v_add_u32_e32 v174, s23, v173
	v_mad_u32_u24 v187, v173, s26, v70
	v_lshlrev_b32_e32 v176, 7, v174
	v_cmp_gt_u32_e32 vcc, s20, v174
	s_nop 1
	v_cndmask_b32_e32 v163, -1, v187, vcc
	s_and_saveexec_b64 s[18:19], vcc
	v_lshl_add_u64 v[178:179], v[188:189], 0, v[176:177]
	global_load_dwordx4 v[132:135], v[178:179], off
	s_mov_b64 exec, s[18:19]
	v_add_u32_e32 v172, 2048, v67
	v_ashrrev_i32_e32 v173, 3, v172
	v_add_u32_e32 v174, s23, v173
	v_cmp_gt_u32_e32 vcc, 0x100, v67
	s_nop 1
	v_cndmask_b32_e32 v174, -1, v174, vcc
	v_mad_u32_u24 v187, v173, s26, v70
	v_lshlrev_b32_e32 v176, 7, v174
	v_cmp_gt_u32_e32 vcc, s20, v174
	s_nop 1
	v_cndmask_b32_e32 v164, -1, v187, vcc
	s_and_saveexec_b64 s[18:19], vcc
	v_lshl_add_u64 v[178:179], v[188:189], 0, v[176:177]
	global_load_dwordx4 v[136:139], v[178:179], off
	s_mov_b64 exec, s[18:19]
	s_mov_b32 s18, 0x38e38e39
	s_movk_i32 s26, 0xfee0
	s_movk_i32 s27, 0x250
	s_movk_i32 s19, 0xfdc0
	v_mov_b32_e32 v172, v67
	v_mul_hi_i32 v175, v172, s18
	v_lshrrev_b32_e32 v180, 31, v175
	v_ashrrev_i32_e32 v175, 3, v175
	v_add_u32_e32 v183, v175, v180
	v_mul_lo_u32 v181, v183, s26
	v_lshlrev_b32_e32 v182, 3, v172
	v_add3_u32 v174, s23, v182, v181
	v_mul_lo_u32 v184, v183, s27
	v_mul_lo_u32 v185, v183, s19
	v_lshl_add_u32 v185, v172, 4, v185
	v_and_b32_e32 v185, 0xffffffe0, v185
	v_and_b32_e32 v186, 8, v182
	v_add3_u32 v187, v184, v185, v186
	v_add_u32_e32 v187, 0xa000, v187
	v_lshlrev_b32_e32 v176, 13, v183
	v_lshl_add_u32 v176, v174, 1, v176
	v_cmp_gt_u32_e32 vcc, s20, v174
	s_nop 1
	v_cndmask_b32_e32 v165, -1, v187, vcc
	s_and_saveexec_b64 s[14:15], vcc
	v_lshl_add_u64 v[178:179], s[16:17], 0, v[176:177]
	global_load_dwordx4 v[140:143], v[178:179], off
	s_mov_b64 exec, s[14:15]
	v_add_u32_e32 v172, 512, v67
	v_mul_hi_i32 v175, v172, s18
	v_lshrrev_b32_e32 v180, 31, v175
	v_ashrrev_i32_e32 v175, 3, v175
	v_add_u32_e32 v183, v175, v180
	v_mul_lo_u32 v181, v183, s26
	v_lshlrev_b32_e32 v182, 3, v172
	v_add3_u32 v174, s23, v182, v181
	v_mul_lo_u32 v184, v183, s27
	v_mul_lo_u32 v185, v183, s19
	v_lshl_add_u32 v185, v172, 4, v185
	v_and_b32_e32 v185, 0xffffffe0, v185
	v_and_b32_e32 v186, 8, v182
	v_add3_u32 v187, v184, v185, v186
	v_add_u32_e32 v187, 0xa000, v187
	v_lshlrev_b32_e32 v176, 13, v183
	v_lshl_add_u32 v176, v174, 1, v176
	v_cmp_gt_u32_e32 vcc, s20, v174
	s_nop 1
	v_cndmask_b32_e32 v166, -1, v187, vcc
	s_and_saveexec_b64 s[14:15], vcc
	v_lshl_add_u64 v[178:179], s[16:17], 0, v[176:177]
	global_load_dwordx4 v[144:147], v[178:179], off
	s_mov_b64 exec, s[14:15]
	v_add_u32_e32 v172, 1024, v67
	v_mul_hi_i32 v175, v172, s18
	v_lshrrev_b32_e32 v180, 31, v175
	v_ashrrev_i32_e32 v175, 3, v175
	v_add_u32_e32 v183, v175, v180
	v_mul_lo_u32 v181, v183, s26
	v_lshlrev_b32_e32 v182, 3, v172
	v_add3_u32 v174, s23, v182, v181
	v_mul_lo_u32 v184, v183, s27
	v_mul_lo_u32 v185, v183, s19
	v_lshl_add_u32 v185, v172, 4, v185
	v_and_b32_e32 v185, 0xffffffe0, v185
	v_and_b32_e32 v186, 8, v182
	v_add3_u32 v187, v184, v185, v186
	v_add_u32_e32 v187, 0xa000, v187
	v_lshlrev_b32_e32 v176, 13, v183
	v_lshl_add_u32 v176, v174, 1, v176
	v_cmp_gt_u32_e32 vcc, s20, v174
	s_nop 1
	v_cndmask_b32_e32 v167, -1, v187, vcc
	s_and_saveexec_b64 s[14:15], vcc
	v_lshl_add_u64 v[178:179], s[16:17], 0, v[176:177]
	global_load_dwordx4 v[148:151], v[178:179], off
	s_mov_b64 exec, s[14:15]
	v_add_u32_e32 v172, 1536, v67
	v_mul_hi_i32 v175, v172, s18
	v_lshrrev_b32_e32 v180, 31, v175
	v_ashrrev_i32_e32 v175, 3, v175
	v_add_u32_e32 v183, v175, v180
	v_mul_lo_u32 v181, v183, s26
	v_lshlrev_b32_e32 v182, 3, v172
	v_add3_u32 v174, s23, v182, v181
	v_mul_lo_u32 v184, v183, s27
	v_mul_lo_u32 v185, v183, s19
	v_lshl_add_u32 v185, v172, 4, v185
	v_and_b32_e32 v185, 0xffffffe0, v185
	v_and_b32_e32 v186, 8, v182
	v_add3_u32 v187, v184, v185, v186
	v_add_u32_e32 v187, 0xa000, v187
	v_lshlrev_b32_e32 v176, 13, v183
	v_lshl_add_u32 v176, v174, 1, v176
	v_cmp_gt_u32_e32 vcc, s20, v174
	s_nop 1
	v_cndmask_b32_e32 v168, -1, v187, vcc
	s_and_saveexec_b64 s[14:15], vcc
	v_lshl_add_u64 v[178:179], s[16:17], 0, v[176:177]
	global_load_dwordx4 v[152:155], v[178:179], off
	s_mov_b64 exec, s[14:15]
	v_add_u32_e32 v172, 2048, v67
	v_mul_hi_i32 v175, v172, s18
	v_lshrrev_b32_e32 v180, 31, v175
	v_ashrrev_i32_e32 v175, 3, v175
	v_add_u32_e32 v183, v175, v180
	v_mul_lo_u32 v181, v183, s26
	v_lshlrev_b32_e32 v182, 3, v172
	v_add3_u32 v174, s23, v182, v181
	v_cmp_gt_u32_e32 vcc, 0x100, v67
	s_nop 1
	v_cndmask_b32_e32 v174, -1, v174, vcc
	v_mul_lo_u32 v184, v183, s27
	v_mul_lo_u32 v185, v183, s19
	v_lshl_add_u32 v185, v172, 4, v185
	v_and_b32_e32 v185, 0xffffffe0, v185
	v_and_b32_e32 v186, 8, v182
	v_add3_u32 v187, v184, v185, v186
	v_add_u32_e32 v187, 0xa000, v187
	v_lshlrev_b32_e32 v176, 13, v183
	v_lshl_add_u32 v176, v174, 1, v176
	v_cmp_gt_u32_e32 vcc, s20, v174
	s_nop 1
	v_cndmask_b32_e32 v169, -1, v187, vcc
	s_and_saveexec_b64 s[14:15], vcc
	v_lshl_add_u64 v[178:179], s[16:17], 0, v[176:177]
	global_load_dwordx4 v[156:159], v[178:179], off
	s_mov_b64 exec, s[14:15]
	s_waitcnt vmcnt(0)
; #define LAS __attribute__((address_space(3)))
; DI void swa_attn_phase(const Params& p, LAS unsigned char* lds) {
;     ...
;             if (key >= 0 && key < S) *(LAS u32x4*)(lds + row * KSTR + cc * 16) = *(const u32x4*)(Kg + (size_t)key * 64 + cc * 8); }
;         for (int c = tid; c < 2304; c += 512) { const int row = c / 36, cc = c - row * 36, key0 = kstart + cc * 8;
;             if (key0 >= 0 && key0 < S) { const u32x4 v = *(const u32x4*)(Vg + (size_t)row * S + key0);
;                 LAS u32x2* dp = (LAS u32x2*)(lds + VOFF + row * VSTR + (cc >> 1) * 32 + (cc & 1) * 8); dp[0] = (u32x2){v[0], v[1]}; dp[2] = (u32x2){v[2], v[3]}; } }
	v_cmp_ne_u32_e32 vcc, -1, v160
	s_and_saveexec_b64 s[14:15], vcc
	ds_write_b128 v160, v[120:123]
	s_mov_b64 exec, s[14:15]
	v_cmp_ne_u32_e32 vcc, -1, v161
	s_and_saveexec_b64 s[14:15], vcc
	ds_write_b128 v161, v[124:127]
	s_mov_b64 exec, s[14:15]
	v_cmp_ne_u32_e32 vcc, -1, v162
	s_and_saveexec_b64 s[14:15], vcc
	ds_write_b128 v162, v[128:131]
	s_mov_b64 exec, s[14:15]
	v_cmp_ne_u32_e32 vcc, -1, v163
	s_and_saveexec_b64 s[14:15], vcc
	ds_write_b128 v163, v[132:135]
	s_mov_b64 exec, s[14:15]
	v_cmp_ne_u32_e32 vcc, -1, v164
	s_and_saveexec_b64 s[14:15], vcc
	ds_write_b128 v164, v[136:139]
	s_mov_b64 exec, s[14:15]
	v_cmp_ne_u32_e32 vcc, -1, v165
	s_and_saveexec_b64 s[14:15], vcc
	ds_write2_b64 v165, v[140:141], v[142:143] offset0:64 offset1:66
	s_mov_b64 exec, s[14:15]
	v_cmp_ne_u32_e32 vcc, -1, v166
	s_and_saveexec_b64 s[14:15], vcc
	ds_write2_b64 v166, v[144:145], v[146:147] offset0:64 offset1:66
	s_mov_b64 exec, s[14:15]
	v_cmp_ne_u32_e32 vcc, -1, v167
	s_and_saveexec_b64 s[14:15], vcc
	ds_write2_b64 v167, v[148:149], v[150:151] offset0:64 offset1:66
	s_mov_b64 exec, s[14:15]
	v_cmp_ne_u32_e32 vcc, -1, v168
	s_and_saveexec_b64 s[14:15], vcc
	ds_write2_b64 v168, v[152:153], v[154:155] offset0:64 offset1:66
	s_mov_b64 exec, s[14:15]
	v_cmp_ne_u32_e32 vcc, -1, v169
	s_and_saveexec_b64 s[14:15], vcc
	ds_write2_b64 v169, v[156:157], v[158:159] offset0:64 offset1:66
	s_mov_b64 exec, s[14:15]

; #define LAS __attribute__((address_space(3)))
; DI float xmax32(float v) { return fmaxf(v, __shfl_xor(v, 32)); }
;     DI const char* a(const Unit& u) const { return (const char*)(A + (size_t)u.pm * BM * lda); }
;     DI const char* a(const Unit& u) const { return (const char*)(A + (size_t)u.pm * BM * 2048 + (u.pn >> 1) * 512); }
;     DI const char* a(const Unit& u) const { return (const char*)((u.pn < 12 ? A1 : A2) + (size_t)u.pm * BM * 512); }
; template <int NDB, int VSTR>
; DI void softmax_pv(const f32x16& sacc, float& m, float& l, f32x16 (&oacc)[NDB], LAS const unsigned char* vptr) {
;     float mx = sacc[0];
; #pragma unroll
;     for (int i = 1; i < 16; ++i) mx = fmaxf(mx, sacc[i]);
;     mx = xmax32(mx);
;     if (__any(mx > m + 8.0f)) {
; DI void swa_attn_phase(const Params& p, LAS unsigned char* lds) {
;     ...
;         for (int blk = 0; blk < 9; ++blk) {
;             const int k0 = kstart + blk * 32;
;             if (k0 < 0 || k0 >= S) continue;
;             f32x16 sacc;
; #pragma unroll
;             for (int i = 0; i < 16; ++i) sacc[i] = 0.f;
; #pragma unroll
;             for (int ks = 0; ks < 4; ++ks) { const bf16x8 a = *(LAS const bf16x8*)(lds + (blk * 32 + r) * KSTR + ks * 32 + h * 16);
;                 sacc = __builtin_amdgcn_mfma_f32_32x32x16_bf16(a, qf[ks], sacc, 0, 0, 0); }
; #pragma unroll
;             for (int i = 0; i < 16; ++i) { const int key = k0 + (i & 3) + 8 * (i >> 2) + 4 * h;
;                 const int dk = qi - key, dp = pq - p.positions[key];
;                 const float sv = sacc[i] - slope2 * (float)(dp < 0 ? -dp : dp);
;                 sacc[i] = ((dk < 0 ? -dk : dk) <= 128) ? sv : -INFINITY; }
.LBB1_851:
	s_cmpk_gt_u32 s23, 0xfff
	s_cbranch_scc1 .LBB1_850
	v_add_u32_e32 v64, s23, v66
	v_lshl_add_u64 v[80:81], v[64:65], 2, s[10:11]
	ds_read_b128 v[32:35], v93
	ds_read_b128 v[98:101], v93 offset:32
	global_load_dwordx4 v[102:105], v[80:81], off
	global_load_dwordx4 v[108:111], v[80:81], off offset:32
	global_load_dwordx4 v[112:115], v[80:81], off offset:64
	global_load_dwordx4 v[116:119], v[80:81], off offset:96
	s_waitcnt lgkmcnt(0)
	v_mfma_f32_32x32x16_bf16 v[32:47], v[32:35], v[48:51], 0
	s_waitcnt vmcnt(0)
	v_sub_u32_e32 v64, v92, v102
	v_mfma_f32_32x32x16_bf16 v[32:47], v[98:101], v[52:55], v[32:47]
	ds_read_b128 v[98:101], v93 offset:64
	s_waitcnt lgkmcnt(0)
	v_mfma_f32_32x32x16_bf16 v[32:47], v[98:101], v[56:59], v[32:47]
	ds_read_b128 v[98:101], v93 offset:96
	s_waitcnt lgkmcnt(0)
	v_mfma_f32_32x32x16_bf16 v[32:47], v[98:101], v[60:63], v[32:47]
	v_sub_u32_e32 v99, 0, v64
	v_max_i32_e32 v64, v64, v99
	v_cvt_f32_u32_e32 v64, v64
	v_add_u32_e32 v101, s12, v88
	v_add_u32_e32 v98, 0x80, v101
	v_add_u32_e32 v102, 0x78, v101
	s_nop 5
	v_fma_f32 v32, -v96, v64, v32
	v_sub_u32_e32 v64, 0xffffff80, v101
	v_max_i32_e32 v64, v98, v64
	v_sub_u32_e32 v98, v92, v103
	v_sub_u32_e32 v99, 0, v98
	v_max_i32_e32 v98, v98, v99
	v_cvt_f32_u32_e32 v98, v98
	v_cmp_gt_u32_e32 vcc, s22, v64
	v_fma_f32 v33, -v96, v98, v33
	s_nop 0
	v_cndmask_b32_e32 v64, v91, v32, vcc
	v_add_u32_e32 v32, 0x7f, v101
	v_sub_u32_e32 v98, 0xffffff81, v101
	v_max_i32_e32 v32, v32, v98
	v_cmp_gt_u32_e32 vcc, s22, v32
	v_add_u32_e32 v32, 0x7e, v101
	s_nop 0
	v_cndmask_b32_e32 v99, v91, v33, vcc
	v_sub_u32_e32 v33, v92, v104
	v_sub_u32_e32 v98, 0, v33
	v_max_i32_e32 v33, v33, v98
	v_cvt_f32_u32_e32 v33, v33
	v_fma_f32 v33, -v96, v33, v34
	v_sub_u32_e32 v34, 0xffffff82, v101
	v_max_i32_e32 v32, v32, v34
	v_cmp_gt_u32_e32 vcc, s22, v32
	v_add_u32_e32 v32, 0x7d, v101
	s_nop 0
	v_cndmask_b32_e32 v100, v91, v33, vcc
	v_sub_u32_e32 v33, v92, v105
	v_sub_u32_e32 v34, 0, v33
	v_max_i32_e32 v33, v33, v34
	v_cvt_f32_u32_e32 v33, v33
	v_sub_u32_e32 v34, 0xffffff83, v101
	v_max_i32_e32 v32, v32, v34
	v_cmp_gt_u32_e32 vcc, s22, v32
	v_fma_f32 v33, -v96, v33, v35
	s_nop 0
	v_cndmask_b32_e32 v98, v91, v33, vcc
	v_mov_b32_e32 v32, v108
	v_mov_b32_e32 v33, v109
	v_mov_b32_e32 v34, v110
	v_mov_b32_e32 v35, v111
	s_nop 0
	v_sub_u32_e32 v32, v92, v32
	v_sub_u32_e32 v103, 0, v32
	v_max_i32_e32 v32, v32, v103
	v_cvt_f32_u32_e32 v32, v32
	v_sub_u32_e32 v33, v92, v33
	v_fma_f32 v32, -v96, v32, v36
	v_sub_u32_e32 v36, 0xffffff88, v101
	v_max_i32_e32 v36, v102, v36
	v_cmp_gt_u32_e32 vcc, s22, v36
	v_sub_u32_e32 v36, 0, v33
	v_max_i32_e32 v33, v33, v36
	v_cvt_f32_u32_e32 v33, v33
	v_cndmask_b32_e32 v102, v91, v32, vcc
	v_add_u32_e32 v32, 0x77, v101
	v_sub_u32_e32 v36, 0xffffff89, v101
	v_max_i32_e32 v32, v32, v36
	v_fma_f32 v33, -v96, v33, v37
	v_cmp_gt_u32_e32 vcc, s22, v32
	v_add_u32_e32 v32, 0x76, v101
	s_nop 0
	v_cndmask_b32_e32 v103, v91, v33, vcc
	v_sub_u32_e32 v33, v92, v34
	v_sub_u32_e32 v34, 0, v33
	v_max_i32_e32 v33, v33, v34
	v_cvt_f32_u32_e32 v33, v33
	v_sub_u32_e32 v34, 0xffffff8a, v101
	v_max_i32_e32 v32, v32, v34
	v_cmp_gt_u32_e32 vcc, s22, v32
	v_fma_f32 v33, -v96, v33, v38
	v_add_u32_e32 v32, 0x75, v101
	v_cndmask_b32_e32 v36, v91, v33, vcc
	v_sub_u32_e32 v33, v92, v35
	v_sub_u32_e32 v34, 0, v33
	v_max_i32_e32 v33, v33, v34
	v_cvt_f32_u32_e32 v33, v33
	v_sub_u32_e32 v34, 0xffffff8b, v101
	v_max_i32_e32 v32, v32, v34
	v_cmp_gt_u32_e32 vcc, s22, v32
	v_fma_f32 v33, -v96, v33, v39
	v_add_u32_e32 v38, 0x70, v101
	v_cndmask_b32_e32 v37, v91, v33, vcc
	v_mov_b32_e32 v32, v112
	v_mov_b32_e32 v33, v113
	v_mov_b32_e32 v34, v114
	v_mov_b32_e32 v35, v115
	s_nop 0
	v_sub_u32_e32 v32, v92, v32
	v_sub_u32_e32 v39, 0, v32
	v_max_i32_e32 v32, v32, v39
	v_sub_u32_e32 v39, 0xffffff90, v101
	v_cvt_f32_u32_e32 v32, v32
	v_max_i32_e32 v38, v38, v39
	v_sub_u32_e32 v33, v92, v33
	v_cmp_gt_u32_e32 vcc, s22, v38
	v_sub_u32_e32 v38, 0, v33
	v_max_i32_e32 v33, v33, v38
	v_cvt_f32_u32_e32 v33, v33
	v_fma_f32 v32, -v96, v32, v40
	v_cndmask_b32_e32 v39, v91, v32, vcc
	v_add_u32_e32 v32, 0x6f, v101
	v_sub_u32_e32 v38, 0xffffff91, v101
	v_max_i32_e32 v32, v32, v38
	v_fma_f32 v33, -v96, v33, v41
	v_cmp_gt_u32_e32 vcc, s22, v32
	v_add_u32_e32 v32, 0x6e, v101
	s_nop 0
	v_cndmask_b32_e32 v40, v91, v33, vcc
	v_sub_u32_e32 v33, v92, v34
	v_sub_u32_e32 v34, 0, v33
	v_max_i32_e32 v33, v33, v34
	v_cvt_f32_u32_e32 v33, v33
	v_sub_u32_e32 v34, 0xffffff92, v101
	v_max_i32_e32 v32, v32, v34
	v_cmp_gt_u32_e32 vcc, s22, v32
	v_fma_f32 v33, -v96, v33, v42
	v_add_u32_e32 v32, 0x6d, v101
	v_cndmask_b32_e32 v38, v91, v33, vcc
	v_sub_u32_e32 v33, v92, v35
	v_sub_u32_e32 v34, 0, v33
	v_max_i32_e32 v33, v33, v34
	v_cvt_f32_u32_e32 v33, v33
	v_sub_u32_e32 v34, 0xffffff93, v101
	v_max_i32_e32 v32, v32, v34
	v_cmp_gt_u32_e32 vcc, s22, v32
	v_fma_f32 v33, -v96, v33, v43
	v_add_u32_e32 v42, 0x68, v101
	v_cndmask_b32_e32 v41, v91, v33, vcc
	v_mov_b32_e32 v32, v116
	v_mov_b32_e32 v33, v117
	v_mov_b32_e32 v34, v118
	v_mov_b32_e32 v35, v119
	s_nop 0
	v_sub_u32_e32 v32, v92, v32
	v_sub_u32_e32 v43, 0, v32
	v_max_i32_e32 v32, v32, v43
	v_sub_u32_e32 v43, 0xffffff98, v101
	v_sub_u32_e32 v33, v92, v33
	v_cvt_f32_u32_e32 v32, v32
	v_max_i32_e32 v42, v42, v43
	v_sub_u32_e32 v43, 0, v33
	v_cmp_gt_u32_e32 vcc, s22, v42
	v_add_u32_e32 v42, 0x67, v101
	v_max_i32_e32 v33, v33, v43
	v_sub_u32_e32 v43, 0xffffff99, v101
	v_sub_u32_e32 v34, v92, v34
	v_cvt_f32_u32_e32 v33, v33
	v_max_i32_e32 v42, v42, v43
	v_sub_u32_e32 v43, 0, v34
	v_max_i32_e32 v34, v34, v43
	v_fma_f32 v32, -v96, v32, v44
	v_cvt_f32_u32_e32 v34, v34
	v_cndmask_b32_e32 v32, v91, v32, vcc
	v_cmp_gt_u32_e32 vcc, s22, v42
	v_add_u32_e32 v42, 0x66, v101
	v_sub_u32_e32 v43, 0xffffff9a, v101
	v_sub_u32_e32 v35, v92, v35
	v_fma_f32 v33, -v96, v33, v45
	v_max_i32_e32 v42, v42, v43
	v_sub_u32_e32 v43, 0, v35
	v_cndmask_b32_e32 v33, v91, v33, vcc
	v_cmp_gt_u32_e32 vcc, s22, v42
	v_add_u32_e32 v42, 0x65, v101
	v_max_i32_e32 v35, v35, v43
	v_sub_u32_e32 v43, 0xffffff9b, v101
	v_fma_f32 v34, -v96, v34, v46
	v_max_i32_e32 v42, v42, v43
	v_cndmask_b32_e32 v34, v91, v34, vcc
	v_cmp_gt_u32_e32 vcc, s22, v42
	v_max_f32_e32 v42, v64, v99
	v_cvt_f32_u32_e32 v35, v35
	v_max3_f32 v42, v42, v100, v98
	v_max3_f32 v42, v42, v102, v103
	v_max3_f32 v42, v42, v36, v37
	v_max3_f32 v42, v42, v39, v40
	v_fma_f32 v35, -v96, v35, v47
	v_max3_f32 v42, v42, v38, v41
	v_cndmask_b32_e32 v35, v91, v35, vcc
	v_max3_f32 v42, v42, v32, v33
	v_max3_f32 v42, v42, v34, v35
	ds_bpermute_b32 v43, v83, v42
	s_waitcnt lgkmcnt(0)
	v_max_f32_e32 v43, v43, v43
	v_max_f32_e32 v42, v42, v43
	v_add_f32_e32 v43, 0x41000000, v97
	v_cmp_gt_f32_e32 vcc, v42, v43
	s_cbranch_vccz .LBB1_849
; DI float fast_exp2(float x) { return __builtin_amdgcn_exp2f(x); }
; template <int NDB, int VSTR>
; DI void softmax_pv(const f32x16& sacc, float& m, float& l, f32x16 (&oacc)[NDB], LAS const unsigned char* vptr) {
;     ...
;         const float mn = fmaxf(m, mx), alpha = fast_exp2(m - mn);
;         l *= alpha; m = mn;
; #pragma unroll
;         for (int db = 0; db < NDB; ++db)
; #pragma unroll
;             for (int i = 0; i < 16; ++i) oacc[db][i] *= alpha;
;     }
	v_max_f32_e32 v42, v42, v42
	v_max_f32_e32 v43, v97, v97
	v_max_f32_e32 v43, v43, v42
	v_sub_f32_e32 v42, v97, v43
	v_exp_f32_e32 v42, v42
	v_mov_b32_e32 v97, v43
	v_mul_f32_e32 v75, v75, v42
	v_pk_mul_f32 v[14:15], v[14:15], v[42:43] op_sel_hi:[1,0]
	v_pk_mul_f32 v[12:13], v[12:13], v[42:43] op_sel_hi:[1,0]
	v_pk_mul_f32 v[10:11], v[10:11], v[42:43] op_sel_hi:[1,0]
	v_pk_mul_f32 v[8:9], v[8:9], v[42:43] op_sel_hi:[1,0]
	v_pk_mul_f32 v[6:7], v[6:7], v[42:43] op_sel_hi:[1,0]
	v_pk_mul_f32 v[4:5], v[4:5], v[42:43] op_sel_hi:[1,0]
	v_pk_mul_f32 v[2:3], v[2:3], v[42:43] op_sel_hi:[1,0]
	v_pk_mul_f32 v[0:1], v[0:1], v[42:43] op_sel_hi:[1,0]
	v_pk_mul_f32 v[30:31], v[30:31], v[42:43] op_sel_hi:[1,0]
	v_pk_mul_f32 v[28:29], v[28:29], v[42:43] op_sel_hi:[1,0]
	v_pk_mul_f32 v[26:27], v[26:27], v[42:43] op_sel_hi:[1,0]
	v_pk_mul_f32 v[24:25], v[24:25], v[42:43] op_sel_hi:[1,0]
	v_pk_mul_f32 v[22:23], v[22:23], v[42:43] op_sel_hi:[1,0]
	v_pk_mul_f32 v[20:21], v[20:21], v[42:43] op_sel_hi:[1,0]
	v_pk_mul_f32 v[18:19], v[18:19], v[42:43] op_sel_hi:[1,0]
	v_pk_mul_f32 v[16:17], v[16:17], v[42:43] op_sel_hi:[1,0]
	s_branch .LBB1_849
